# grid barrier before the sample-row final LayerNorm replaced by a unit counter; workgroups without LN rows exit
# baseline (speedup 1.0000x reference)
; template <class Epi, bool PAIR>
; __device__ __forceinline__ void small_gemm(LAS unsigned char* lds, const bf16_t* A, int lda, const bf16_t* B, int ldb, int K, int nrg, int nct, size_t row_base, int col_base, const Epi& E, int G, int c) {
;     ...
; #pragma unroll 4
;         for (int ks = 0; ks < nks; ++ks) {
;             bf16x8 a[4], b[4];
; #pragma unroll
;             for (int mi = 0; mi < 4; ++mi) a[mi] = *(const bf16x8*)(ap + (size_t)(mi * 16) * lda + ks * 32);
; #pragma unroll
;             for (int ni = 0; ni < 4; ++ni) { const int roff = PAIR ? ((ni & 1) * 16 + (ni >> 1) * 128) : ni * 16; b[ni] = *(const bf16x8*)(bp + (size_t)roff * ldb + ks * 32); }
; #pragma unroll
;             for (int mi = 0; mi < 4; ++mi)
; #pragma unroll
;                 for (int ni = 0; ni < 4; ++ni) acc[mi][ni] = __builtin_amdgcn_mfma_f32_16x16x32_bf16(b[ni], a[mi], acc[mi][ni], 0, 0, 0);
;         }
.LBB0_1487:
	v_lshl_add_u64 v[132:133], v[68:69], 0, s[6:7]
	v_add_co_u32_e32 v136, vcc, s1, v132
	v_lshl_add_u64 v[84:85], v[70:71], 0, s[6:7]
	s_nop 0
	v_addc_co_u32_e32 v137, vcc, 0, v133, vcc
	v_add_co_u32_e32 v138, vcc, s3, v132
	s_add_u32 s6, s6, 0x100
	s_nop 0
	v_addc_co_u32_e32 v139, vcc, 0, v133, vcc
	v_add_co_u32_e32 v140, vcc, s9, v84
	s_addc_u32 s7, s7, 0
	s_nop 0
	v_addc_co_u32_e32 v141, vcc, 0, v85, vcc
	v_add_co_u32_e32 v142, vcc, s10, v84
	s_cmpk_eq_i32 s6, 0x400
	s_nop 0
	v_addc_co_u32_e32 v143, vcc, 0, v85, vcc
	v_add_co_u32_e32 v144, vcc, s11, v84
	s_nop 1
	v_addc_co_u32_e32 v145, vcc, 0, v85, vcc
	v_add_co_u32_e32 v146, vcc, s12, v84
	s_nop 1
	v_addc_co_u32_e32 v147, vcc, 0, v85, vcc
	global_load_dwordx4 v[84:87], v[140:141], off
	global_load_dwordx4 v[88:91], v[136:137], off
	global_load_dwordx4 v[92:95], v[136:137], off offset:64
	global_load_dwordx4 v[96:99], v[140:141], off offset:64
	global_load_dwordx4 v[100:103], v[142:143], off
	global_load_dwordx4 v[104:107], v[142:143], off offset:64
	global_load_dwordx4 v[108:111], v[144:145], off
	global_load_dwordx4 v[112:115], v[144:145], off offset:64
	global_load_dwordx4 v[116:119], v[146:147], off
	global_load_dwordx4 v[120:123], v[146:147], off offset:64
	v_add_co_u32_e32 v148, vcc, s5, v132
	s_waitcnt vmcnt(8)
	v_mfma_f32_16x16x32_bf16 v[56:59], v[84:87], v[88:91], v[56:59]
	v_addc_co_u32_e32 v149, vcc, 0, v133, vcc
	v_add_co_u32_e32 v150, vcc, s8, v132
	s_waitcnt vmcnt(5)
	v_mfma_f32_16x16x32_bf16 v[44:47], v[100:103], v[88:91], v[44:47]
	v_addc_co_u32_e32 v151, vcc, 0, v133, vcc
	s_waitcnt vmcnt(3)
	v_mfma_f32_16x16x32_bf16 v[24:27], v[108:111], v[88:91], v[24:27]
	s_waitcnt vmcnt(1)
	v_mfma_f32_16x16x32_bf16 v[16:19], v[116:119], v[88:91], v[16:19]
	global_load_dwordx4 v[88:91], v[138:139], off
	global_load_dwordx4 v[124:127], v[138:139], off offset:64
	v_mfma_f32_16x16x32_bf16 v[56:59], v[96:99], v[92:95], v[56:59]
	v_mfma_f32_16x16x32_bf16 v[44:47], v[104:107], v[92:95], v[44:47]
	v_mfma_f32_16x16x32_bf16 v[24:27], v[112:115], v[92:95], v[24:27]
	s_waitcnt vmcnt(2)
	v_mfma_f32_16x16x32_bf16 v[16:19], v[120:123], v[92:95], v[16:19]
	s_waitcnt vmcnt(1)
	v_mfma_f32_16x16x32_bf16 v[12:15], v[84:87], v[88:91], v[12:15]
	v_mfma_f32_16x16x32_bf16 v[8:11], v[100:103], v[88:91], v[8:11]
	v_mfma_f32_16x16x32_bf16 v[4:7], v[108:111], v[88:91], v[4:7]
	v_mfma_f32_16x16x32_bf16 v[0:3], v[116:119], v[88:91], v[0:3]
	global_load_dwordx4 v[88:91], v[148:149], off
	global_load_dwordx4 v[128:131], v[148:149], off offset:64
	global_load_dwordx4 v[132:135], v[150:151], off
	s_waitcnt vmcnt(3)
	v_mfma_f32_16x16x32_bf16 v[12:15], v[96:99], v[124:127], v[12:15]
	v_mfma_f32_16x16x32_bf16 v[8:11], v[104:107], v[124:127], v[8:11]
	v_mfma_f32_16x16x32_bf16 v[4:7], v[112:115], v[124:127], v[4:7]
	v_mfma_f32_16x16x32_bf16 v[0:3], v[120:123], v[124:127], v[0:3]
	s_waitcnt vmcnt(2)
	v_mfma_f32_16x16x32_bf16 v[20:23], v[84:87], v[88:91], v[20:23]
	v_mfma_f32_16x16x32_bf16 v[28:31], v[100:103], v[88:91], v[28:31]
	v_mfma_f32_16x16x32_bf16 v[32:35], v[108:111], v[88:91], v[32:35]
	v_mfma_f32_16x16x32_bf16 v[36:39], v[116:119], v[88:91], v[36:39]
	global_load_dwordx4 v[88:91], v[150:151], off offset:64
	s_waitcnt vmcnt(1)
	v_mfma_f32_16x16x32_bf16 v[40:43], v[84:87], v[132:135], v[40:43]
	global_load_dwordx4 v[84:87], v[140:141], off offset:128
	v_mfma_f32_16x16x32_bf16 v[48:51], v[100:103], v[132:135], v[48:51]
	v_mfma_f32_16x16x32_bf16 v[52:55], v[108:111], v[132:135], v[52:55]
	v_mfma_f32_16x16x32_bf16 v[60:63], v[116:119], v[132:135], v[60:63]
	v_mfma_f32_16x16x32_bf16 v[20:23], v[96:99], v[128:131], v[20:23]
	v_mfma_f32_16x16x32_bf16 v[28:31], v[104:107], v[128:131], v[28:31]
	v_mfma_f32_16x16x32_bf16 v[32:35], v[112:115], v[128:131], v[32:35]
	v_mfma_f32_16x16x32_bf16 v[36:39], v[120:123], v[128:131], v[36:39]
	s_waitcnt vmcnt(1)
	v_mfma_f32_16x16x32_bf16 v[40:43], v[96:99], v[88:91], v[40:43]
	v_mfma_f32_16x16x32_bf16 v[48:51], v[104:107], v[88:91], v[48:51]
	v_mfma_f32_16x16x32_bf16 v[52:55], v[112:115], v[88:91], v[52:55]
	v_mfma_f32_16x16x32_bf16 v[60:63], v[120:123], v[88:91], v[60:63]
	global_load_dwordx4 v[88:91], v[136:137], off offset:128
	global_load_dwordx4 v[92:95], v[136:137], off offset:192
	global_load_dwordx4 v[96:99], v[140:141], off offset:192
	global_load_dwordx4 v[100:103], v[142:143], off offset:128
	global_load_dwordx4 v[104:107], v[142:143], off offset:192
	global_load_dwordx4 v[108:111], v[144:145], off offset:128
	global_load_dwordx4 v[112:115], v[144:145], off offset:192
	global_load_dwordx4 v[116:119], v[146:147], off offset:128
	global_load_dwordx4 v[120:123], v[146:147], off offset:192
	s_waitcnt vmcnt(8)
	v_mfma_f32_16x16x32_bf16 v[56:59], v[84:87], v[88:91], v[56:59]
	s_waitcnt vmcnt(5)
	v_mfma_f32_16x16x32_bf16 v[44:47], v[100:103], v[88:91], v[44:47]
	s_waitcnt vmcnt(3)
	v_mfma_f32_16x16x32_bf16 v[24:27], v[108:111], v[88:91], v[24:27]
	s_waitcnt vmcnt(1)
	v_mfma_f32_16x16x32_bf16 v[16:19], v[116:119], v[88:91], v[16:19]
	global_load_dwordx4 v[88:91], v[138:139], off offset:128
	global_load_dwordx4 v[124:127], v[138:139], off offset:192
	s_waitcnt vmcnt(1)
	v_mfma_f32_16x16x32_bf16 v[12:15], v[84:87], v[88:91], v[12:15]
	v_mfma_f32_16x16x32_bf16 v[8:11], v[100:103], v[88:91], v[8:11]
	v_mfma_f32_16x16x32_bf16 v[4:7], v[108:111], v[88:91], v[4:7]
	v_mfma_f32_16x16x32_bf16 v[0:3], v[116:119], v[88:91], v[0:3]
	global_load_dwordx4 v[88:91], v[148:149], off offset:128
	global_load_dwordx4 v[128:131], v[148:149], off offset:192
	global_load_dwordx4 v[132:135], v[150:151], off offset:128
	s_waitcnt vmcnt(2)
; #define LAS __attribute__((address_space(3)))
;     __device__ __forceinline__ void small(size_t row, int col, const f32x4 v0, const f32x4 v1) const { *(u32x4*)(Ub + row * DSSM + col) = pack8(v0, v1); }
;     __device__ __forceinline__ void small(size_t row, int col, const f32x4 v0, const f32x4 v1) const {
;         const f32x4 z = (f32x4){0.f, 0.f, 0.f, 0.f};
;         float mean = 0.f, rstd = 0.f;
;         if constexpr (CONS) { float s0, q0, s1, q1; stats_of(st_in, row, 0, s0, q0); stats_of(st_in, row, 1, s1, q1); mean = (s0 + s1) * (1.f / DM); rstd = __builtin_amdgcn_rsqf(fmaxf((q0 + q1) * (1.f / DM) - mean * mean, 0.f) + LN_EPS); }
;         float s = 0.f, ss = 0.f;
;         piece(row, col, v0, v1, CONS ? *(const f32x4*)(va + col) : z, CONS ? *(const f32x4*)(va + col + 4) : z, CONS ? *(const f32x4*)(vb + col) : z, CONS ? *(const f32x4*)(vb + col + 4) : z,
;               (MODE == 5) ? *(const f32x4*)(bias + col) : z, (MODE == 5) ? *(const f32x4*)(bias + col + 4) : z, mean, rstd, s, ss);
; template <class Epi, bool PAIR>
; __device__ __forceinline__ void small_gemm(LAS unsigned char* lds, const bf16_t* A, int lda, const bf16_t* B, int ldb, int K, int nrg, int nct, size_t row_base, int col_base, const Epi& E, int G, int c) {
;     ...
;         __syncthreads();
; #pragma unroll
;         for (int mi = 0; mi < 4; ++mi)
; #pragma unroll
;             for (int ni = 0; ni < 4; ++ni) *(LAS f32x4*)(red + (wid * 64 + mi * 16 + fr) * 68 + ni * 16 + 4 * fq) = acc[mi][ni];
;         __syncthreads();
;         if constexpr (!PAIR) {
;             const int r = tid >> 3, pc = tid & 7; f32x4 v0 = (f32x4){0.f, 0.f, 0.f, 0.f}, v1 = v0;
; #pragma unroll
;             for (int w = 0; w < 8; ++w) { v0 += *(const LAS f32x4*)(red + (w * 64 + r) * 68 + pc * 8); v1 += *(const LAS f32x4*)(red + (w * 64 + r) * 68 + pc * 8 + 4); }
;             E.small(row_base + rg * 64 + r, col_base + ct * 64 + pc * 8, v0, v1);
	v_mfma_f32_16x16x32_bf16 v[20:23], v[84:87], v[88:91], v[20:23]
	v_mfma_f32_16x16x32_bf16 v[28:31], v[100:103], v[88:91], v[28:31]
	v_mfma_f32_16x16x32_bf16 v[32:35], v[108:111], v[88:91], v[32:35]
	v_mfma_f32_16x16x32_bf16 v[36:39], v[116:119], v[88:91], v[36:39]
	global_load_dwordx4 v[88:91], v[150:151], off offset:192
	s_waitcnt vmcnt(1)
	v_mfma_f32_16x16x32_bf16 v[40:43], v[84:87], v[132:135], v[40:43]
	v_mfma_f32_16x16x32_bf16 v[48:51], v[100:103], v[132:135], v[48:51]
	v_mfma_f32_16x16x32_bf16 v[52:55], v[108:111], v[132:135], v[52:55]
	v_mfma_f32_16x16x32_bf16 v[60:63], v[116:119], v[132:135], v[60:63]
	v_mfma_f32_16x16x32_bf16 v[56:59], v[96:99], v[92:95], v[56:59]
	v_mfma_f32_16x16x32_bf16 v[44:47], v[104:107], v[92:95], v[44:47]
	v_mfma_f32_16x16x32_bf16 v[24:27], v[112:115], v[92:95], v[24:27]
	v_mfma_f32_16x16x32_bf16 v[16:19], v[120:123], v[92:95], v[16:19]
	v_mfma_f32_16x16x32_bf16 v[12:15], v[96:99], v[124:127], v[12:15]
	v_mfma_f32_16x16x32_bf16 v[8:11], v[104:107], v[124:127], v[8:11]
	v_mfma_f32_16x16x32_bf16 v[4:7], v[112:115], v[124:127], v[4:7]
	v_mfma_f32_16x16x32_bf16 v[0:3], v[120:123], v[124:127], v[0:3]
	v_mfma_f32_16x16x32_bf16 v[20:23], v[96:99], v[128:131], v[20:23]
	v_mfma_f32_16x16x32_bf16 v[28:31], v[104:107], v[128:131], v[28:31]
	v_mfma_f32_16x16x32_bf16 v[32:35], v[112:115], v[128:131], v[32:35]
	v_mfma_f32_16x16x32_bf16 v[36:39], v[120:123], v[128:131], v[36:39]
	s_waitcnt vmcnt(0)
	v_mfma_f32_16x16x32_bf16 v[40:43], v[96:99], v[88:91], v[40:43]
	v_mfma_f32_16x16x32_bf16 v[48:51], v[104:107], v[88:91], v[48:51]
	v_mfma_f32_16x16x32_bf16 v[52:55], v[112:115], v[88:91], v[52:55]
	v_mfma_f32_16x16x32_bf16 v[60:63], v[120:123], v[88:91], v[60:63]
	s_cbranch_scc0 .LBB0_1487
	s_lshl_b32 s6, s14, 2
	s_sub_i32 s6, s2, s6
	v_lshl_add_u32 v92, s6, 6, v73
	v_ashrrev_i32_e32 v93, 31, v92
	s_barrier
	ds_write_b128 v64, v[56:59]
	ds_write_b128 v64, v[44:47] offset:64
	ds_write_b128 v64, v[24:27] offset:128
	ds_write_b128 v64, v[16:19] offset:192
	ds_write_b128 v64, v[12:15] offset:4352
	ds_write_b128 v64, v[8:11] offset:4416
	ds_write_b128 v64, v[4:7] offset:4480
	ds_write_b128 v64, v[0:3] offset:4544
	ds_write_b128 v64, v[20:23] offset:8704
	ds_write_b128 v64, v[28:31] offset:8768
	ds_write_b128 v64, v[32:35] offset:8832
	ds_write_b128 v64, v[36:39] offset:8896
	ds_write_b128 v64, v[40:43] offset:13056
	ds_write_b128 v64, v[48:51] offset:13120
	ds_write_b128 v64, v[52:55] offset:13184
	ds_write_b128 v64, v[60:63] offset:13248
	v_lshlrev_b64 v[0:1], 7, v[92:93]
	v_lshl_add_u64 v[32:33], s[90:91], 0, v[0:1]
	s_waitcnt lgkmcnt(0)
	s_barrier
	global_load_dwordx4 v[0:3], v[32:33], off
	global_load_dwordx4 v[4:7], v[32:33], off offset:16
	global_load_dwordx4 v[8:11], v[32:33], off offset:32
	global_load_dwordx4 v[12:15], v[32:33], off offset:48
	global_load_dwordx4 v[16:19], v[32:33], off offset:64
	global_load_dwordx4 v[20:23], v[32:33], off offset:80
	global_load_dwordx4 v[24:27], v[32:33], off offset:96
	global_load_dwordx4 v[28:31], v[32:33], off offset:112
	ds_read_b128 v[32:35], v75
	ds_read_b128 v[36:39], v75 offset:16
	v_or_b32_e32 v44, s13, v74
	v_lshlrev_b64 v[40:41], 11, v[92:93]
	v_ashrrev_i32_e32 v45, 31, v44
	v_lshl_add_u64 v[40:41], s[88:89], 0, v[40:41]
	v_lshl_add_u64 v[40:41], v[44:45], 1, v[40:41]
	v_readlane_b32 s16, v254, 3
	global_load_dwordx4 v[40:43], v[40:41], off
	s_waitcnt lgkmcnt(1)
	v_pk_add_f32 v[60:61], v[34:35], 0 op_sel_hi:[1,0]
	v_pk_add_f32 v[68:69], v[32:33], 0 op_sel_hi:[1,0]
	s_waitcnt lgkmcnt(0)
	v_pk_add_f32 v[70:71], v[38:39], 0 op_sel_hi:[1,0]
	v_pk_add_f32 v[84:85], v[36:37], 0 op_sel_hi:[1,0]
	ds_read_b128 v[32:35], v75 offset:17408
	ds_read_b128 v[36:39], v75 offset:17424
	v_readlane_b32 s20, v254, 7
	v_readlane_b32 s21, v254, 8
	v_readlane_b32 s22, v254, 9
	v_readlane_b32 s23, v254, 10
	v_readlane_b32 s28, v254, 15
	v_readlane_b32 s29, v254, 16
	v_readlane_b32 s30, v254, 17
	v_readlane_b32 s31, v254, 18
	s_mov_b64 s[20:21], s[28:29]
	v_lshlrev_b64 v[94:95], 2, v[44:45]
	s_mov_b64 s[22:23], s[30:31]
	v_lshl_add_u64 v[52:53], s[20:21], 0, v[94:95]
	v_lshl_add_u64 v[62:63], s[22:23], 0, v[94:95]
	global_load_dwordx4 v[44:47], v[52:53], off offset:16
	global_load_dwordx4 v[48:51], v[52:53], off
	s_nop 0
	global_load_dwordx4 v[52:55], v[62:63], off offset:16
	global_load_dwordx4 v[56:59], v[62:63], off
	s_waitcnt lgkmcnt(1)
	v_pk_add_f32 v[86:87], v[60:61], v[34:35]
	ds_read_b128 v[60:63], v75 offset:34816
	v_pk_add_f32 v[68:69], v[68:69], v[32:33]
	ds_read_b128 v[32:35], v75 offset:34832
	s_waitcnt lgkmcnt(2)
	v_pk_add_f32 v[38:39], v[70:71], v[38:39]
	v_pk_add_f32 v[88:89], v[84:85], v[36:37]
	s_waitcnt lgkmcnt(1)
	v_pk_add_f32 v[90:91], v[86:87], v[62:63]
	v_pk_add_f32 v[96:97], v[68:69], v[60:61]
	s_waitcnt lgkmcnt(0)
	v_pk_add_f32 v[98:99], v[38:39], v[34:35]
	v_lshl_add_u64 v[38:39], s[50:51], 0, v[94:95]
	ds_read_b128 v[34:37], v75 offset:52224
	ds_read_b128 v[60:63], v75 offset:52240
	global_load_dwordx4 v[68:71], v[38:39], off offset:16
	global_load_dwordx4 v[84:87], v[38:39], off
	v_pk_add_f32 v[88:89], v[88:89], v[32:33]
	s_add_i32 s2, s2, s92
	s_waitcnt lgkmcnt(1)
	v_pk_add_f32 v[90:91], v[90:91], v[36:37]
	ds_read_b128 v[36:39], v76
	v_pk_add_f32 v[96:97], v[96:97], v[34:35]
	ds_read_b128 v[32:35], v77
	s_waitcnt lgkmcnt(2)
	v_pk_add_f32 v[98:99], v[98:99], v[62:63]
	v_pk_add_f32 v[88:89], v[88:89], v[60:61]
	ds_read_b128 v[60:63], v78
	s_waitcnt lgkmcnt(2)
	v_pk_add_f32 v[96:97], v[96:97], v[36:37]
	s_waitcnt lgkmcnt(1)
	v_pk_add_f32 v[98:99], v[98:99], v[34:35]
	ds_read_b128 v[34:37], v79
	v_pk_add_f32 v[38:39], v[90:91], v[38:39]
	v_pk_add_f32 v[32:33], v[88:89], v[32:33]
	ds_read_b128 v[88:91], v80
	s_waitcnt lgkmcnt(2)
; __device__ __forceinline__ void unpack8(const u32x4 w, f32x4& a, f32x4& b) { a = (f32x4){bf_lo(w.x), bf_hi(w.x), bf_lo(w.y), bf_hi(w.y)}; b = (f32x4){bf_lo(w.z), bf_hi(w.z), bf_lo(w.w), bf_hi(w.w)}; }
; __device__ __forceinline__ Frame fresh(const Frame& F0) { Frame F = F0; int t = threadIdx.x; asm volatile("" : "+v"(t)); F.tid = t; F.lane = t & 63; F.wave = __builtin_amdgcn_readfirstlane(t >> 6); return F; }
;     __device__ __forceinline__ void piece(size_t row, int col, f32x4 v0, f32x4 v1, const f32x4 a0, const f32x4 a1, const f32x4 b0, const f32x4 b1, const f32x4 c0, const f32x4 c1,
;                                           float mean, float rstd, float& s, float& ss) const {
;     ...
;         if constexpr (RECOMP) { f32x4 r0, r1; unpack8(*(const u32x4*)(Tin + row * DM + col), r0, r1);
;             r0 = (r0 - mean) * rstd * a0 + b0; r1 = (r1 - mean) * rstd * a1 + b1; v0 = r0 * ALPHA + v0; v1 = r1 * ALPHA + v1;
;             if constexpr (MODE == 5) { v0 = v0 + c0; v1 = v1 + c1; } }
;         if constexpr (MODE == 4) { v0 = (v0 - a0 * mean) * rstd + b0; v1 = (v1 - a1 * mean) * rstd + b1;
; #pragma unroll
;             for (int e = 0; e < 4; ++e) { const float x = fmaxf(v0[e], 0.f), y = fmaxf(v1[e], 0.f); v0[e] = x * x; v1[e] = y * y; } }
;         if constexpr (PROD) {
; #pragma unroll
;             for (int e = 0; e < 4; ++e) { s += v0[e] + v1[e]; ss += v0[e] * v0[e] + v1[e] * v1[e]; } }
;         if constexpr (MODE == 5) { float* o = (float*)O + row * ldo + col; *(f32x4*)o = v0; *(f32x4*)(o + 4) = v1; }
; __device__ __forceinline__ void ln_f32_inplace_phase(const Frame& F0, float* Y, const float* gam, const float* bet) {
;     const Frame F = fresh(F0);
;     const int gw = F.vcu * 8 + F.wave, NGW = F.G * 8;
;     f32x4 g4[4], b4[4];
; #pragma unroll
;     for (int q = 0; q < 4; ++q) { g4[q] = *(const f32x4*)(gam + q * 256 + F.lane * 4); b4[q] = *(const f32x4*)(bet + q * 256 + F.lane * 4); }
;     for (int m0 = gw; m0 < R; m0 += 2 * NGW) {
;         const int m1 = m0 + NGW; const bool ok1 = m1 < R; const int mm1 = ok1 ? m1 : m0;
;         f32x4 v[2][4];
; #pragma unroll
;         for (int q = 0; q < 4; ++q) { v[0][q] = *(const f32x4*)(Y + (size_t)m0 * DM + q * 256 + F.lane * 4); v[1][q] = *(const f32x4*)(Y + (size_t)mm1 * DM + q * 256 + F.lane * 4); }
	v_pk_add_f32 v[38:39], v[38:39], v[62:63]
	v_pk_add_f32 v[60:61], v[96:97], v[60:61]
	s_waitcnt lgkmcnt(1)
	v_pk_add_f32 v[96:97], v[98:99], v[36:37]
	v_pk_add_f32 v[98:99], v[32:33], v[34:35]
	ds_read_b128 v[32:35], v81
	s_waitcnt lgkmcnt(1)
	v_pk_add_f32 v[90:91], v[38:39], v[90:91]
	ds_read_b128 v[36:39], v82
	v_pk_add_f32 v[88:89], v[60:61], v[88:89]
	ds_read_b128 v[60:63], v83
	s_waitcnt lgkmcnt(2)
	v_pk_add_f32 v[32:33], v[98:99], v[32:33]
	v_pk_add_f32 v[34:35], v[96:97], v[34:35]
	s_waitcnt lgkmcnt(1)
	v_pk_add_f32 v[38:39], v[90:91], v[38:39]
	v_pk_add_f32 v[36:37], v[88:89], v[36:37]
	s_waitcnt lgkmcnt(0)
	v_pk_add_f32 v[32:33], v[32:33], v[60:61]
	v_pk_add_f32 v[34:35], v[34:35], v[62:63]
	s_cmp_gt_i32 s2, 63
	v_readlane_b32 s17, v254, 4
	s_waitcnt vmcnt(14)
	v_pk_add_f32 v[0:1], v[0:1], v[2:3]
	s_waitcnt vmcnt(13)
	v_pk_add_f32 v[2:3], v[4:5], v[6:7]
	v_pk_add_f32 v[0:1], v[0:1], 0 op_sel_hi:[1,0]
	v_readlane_b32 s18, v254, 5
	v_pk_add_f32 v[0:1], v[0:1], v[2:3]
	s_waitcnt vmcnt(12)
	v_pk_add_f32 v[2:3], v[8:9], v[10:11]
	s_waitcnt vmcnt(9)
	v_pk_add_f32 v[4:5], v[20:21], v[22:23]
	v_pk_add_f32 v[0:1], v[0:1], v[2:3]
	v_pk_add_f32 v[2:3], v[12:13], v[14:15]
	v_readlane_b32 s19, v254, 6
	v_pk_add_f32 v[0:1], v[0:1], v[2:3]
	v_pk_add_f32 v[2:3], v[16:17], v[18:19]
	v_readlane_b32 s24, v254, 11
	v_pk_add_f32 v[2:3], v[2:3], 0 op_sel_hi:[1,0]
	v_readlane_b32 s25, v254, 12
	v_pk_add_f32 v[2:3], v[2:3], v[4:5]
	s_waitcnt vmcnt(8)
	v_pk_add_f32 v[4:5], v[24:25], v[26:27]
	s_waitcnt vmcnt(6)
	v_lshlrev_b32_e32 v10, 16, v42
	v_pk_add_f32 v[2:3], v[2:3], v[4:5]
	v_pk_add_f32 v[4:5], v[28:29], v[30:31]
	v_and_b32_e32 v11, 0xffff0000, v42
	v_pk_add_f32 v[2:3], v[2:3], v[4:5]
	v_lshlrev_b32_e32 v4, 16, v41
	v_pk_add_f32 v[0:1], v[0:1], v[2:3]
	v_and_b32_e32 v3, 0xffff0000, v40
	v_pk_mul_f32 v[0:1], v[0:1], s[0:1] op_sel_hi:[1,0]
	v_and_b32_e32 v5, 0xffff0000, v41
	v_fma_f32 v1, -v0, v0, v1
	v_max_f32_e32 v1, 0, v1
	v_add_f32_e32 v1, 0x3727c5ac, v1
	v_rsq_f32_e32 v2, v1
	v_lshlrev_b32_e32 v1, 16, v40
	v_lshlrev_b32_e32 v8, 16, v43
	v_and_b32_e32 v9, 0xffff0000, v43
	v_sub_f32_e32 v5, v5, v0
	v_sub_f32_e32 v4, v4, v0
	v_sub_f32_e32 v7, v3, v0
	v_sub_f32_e32 v6, v1, v0
	v_sub_f32_e32 v9, v9, v0
	v_sub_f32_e32 v8, v8, v0
	v_sub_f32_e32 v1, v11, v0
	v_sub_f32_e32 v0, v10, v0
	v_pk_mul_f32 v[4:5], v[2:3], v[4:5] op_sel_hi:[0,1]
	v_pk_mul_f32 v[0:1], v[2:3], v[0:1] op_sel_hi:[0,1]
	v_pk_mul_f32 v[6:7], v[2:3], v[6:7] op_sel_hi:[0,1]
	s_waitcnt vmcnt(2)
	v_pk_fma_f32 v[4:5], v[50:51], v[4:5], v[58:59]
	v_pk_mul_f32 v[2:3], v[2:3], v[8:9] op_sel_hi:[0,1]
	v_pk_fma_f32 v[0:1], v[44:45], v[0:1], v[52:53]
	v_pk_fma_f32 v[2:3], v[46:47], v[2:3], v[54:55]
	v_pk_fma_f32 v[4:5], v[4:5], s[4:5], v[38:39] op_sel_hi:[1,0,1]
	v_pk_fma_f32 v[8:9], v[0:1], s[4:5], v[32:33] op_sel_hi:[1,0,1]
	v_pk_fma_f32 v[6:7], v[48:49], v[6:7], v[56:57]
	v_pk_fma_f32 v[10:11], v[2:3], s[4:5], v[34:35] op_sel_hi:[1,0,1]
	s_waitcnt vmcnt(0)
	v_pk_add_f32 v[2:3], v[86:87], v[4:5]
	v_pk_add_f32 v[4:5], v[68:69], v[8:9]
	v_lshlrev_b64 v[8:9], 12, v[92:93]
	v_pk_fma_f32 v[6:7], v[6:7], s[4:5], v[36:37] op_sel_hi:[1,0,1]
	v_lshl_add_u64 v[8:9], s[56:57], 0, v[8:9]
	v_pk_add_f32 v[0:1], v[84:85], v[6:7]
	v_pk_add_f32 v[6:7], v[70:71], v[10:11]
	v_lshl_add_u64 v[8:9], v[8:9], 0, v[94:95]
	v_readlane_b32 s26, v254, 13
	v_readlane_b32 s27, v254, 14
	global_store_dwordx4 v[8:9], v[0:3], off sc0 sc1
	global_store_dwordx4 v[8:9], v[4:7], off offset:16 sc0 sc1
	s_cbranch_scc0 .LBB0_1486
.LBB0_1489:
	s_barrier
	s_waitcnt vmcnt(0)
	s_barrier
	s_mov_b64 s[0:1], exec
	v_readlane_b32 s4, v254, 20
	v_readlane_b32 s5, v254, 21
	s_and_b64 s[4:5], s[0:1], s[4:5]
	s_mov_b64 exec, s[4:5]
	s_cbranch_execz .Lb10_done
	s_and_b32 s3, s2, 0xff
	s_cmp_lt_u32 s3, 64
	s_cbranch_scc0 .Lb10_done
	v_mov_b32_e32 v0, 0x3b80
	v_mov_b32_e32 v1, 1
	global_atomic_add v0, v1, s[58:59]
.Lb10_done:
	s_mov_b64 exec, s[0:1]
	s_and_b32 s3, s2, 7
	s_cmp_lg_u32 s3, 0
	s_cbranch_scc1 .LBB0_1546
.LBB0_1541:
	s_or_b64 exec, exec, s[0:1]
	s_waitcnt lgkmcnt(0)
	s_barrier
	v_readlane_b32 s1, v254, 56
	v_readfirstlane_b32 s0, v202
	s_ashr_i32 s0, s0, 6
	s_add_i32 s2, s0, s1
	s_add_i32 s2, s2, 0x8000
	s_cmp_gt_i32 s2, 0x80ff
	s_cbranch_scc1 .LBB0_1546
	v_mov_b32_e32 v0, 0x3b80
	s_mov_b32 s3, 0x40000
.Lsmp_p12:
	global_load_dword v1, v0, s[58:59] sc0 sc1
	s_waitcnt vmcnt(0)
	v_readfirstlane_b32 s4, v1
	s_cmpk_ge_u32 s4, 64
	s_cbranch_scc1 .Lsmg_p12
	s_sleep 1
	s_sub_u32 s3, s3, 1
	s_cmp_lg_u32 s3, 0
	s_cbranch_scc1 .Lsmp_p12
.Lsmg_p12:
	buffer_inv sc1
	v_lshlrev_b32_e32 v0, 4, v202
	v_and_b32_e32 v32, 0x3f0, v0
	global_load_dwordx4 v[0:3], v32, s[52:53]
	global_load_dwordx4 v[4:7], v32, s[54:55]
	global_load_dwordx4 v[8:11], v32, s[52:53] offset:1024
	global_load_dwordx4 v[12:15], v32, s[54:55] offset:1024
	global_load_dwordx4 v[16:19], v32, s[52:53] offset:2048
	global_load_dwordx4 v[20:23], v32, s[54:55] offset:2048
	global_load_dwordx4 v[24:27], v32, s[52:53] offset:3072
	global_load_dwordx4 v[28:31], v32, s[54:55] offset:3072
	v_mov_b32_e32 v33, 0
	v_lshl_add_u64 v[64:65], s[56:57], 0, v[32:33]
	v_mbcnt_lo_u32_b32 v32, -1, 0
	v_mbcnt_hi_u32_b32 v32, -1, v32
	v_and_b32_e32 v33, 64, v32
	v_add_u32_e32 v33, 64, v33
	v_xor_b32_e32 v34, 1, v32
	v_cmp_lt_i32_e32 vcc, v34, v33
	v_mov_b32_e32 v74, 0x3727c5ac
	s_nop 0
	v_cndmask_b32_e32 v34, v32, v34, vcc
	v_lshlrev_b32_e32 v68, 2, v34
	v_xor_b32_e32 v34, 2, v32
	v_cmp_lt_i32_e32 vcc, v34, v33
	s_nop 1
	v_cndmask_b32_e32 v34, v32, v34, vcc
	v_lshlrev_b32_e32 v69, 2, v34
	v_xor_b32_e32 v34, 4, v32
	v_cmp_lt_i32_e32 vcc, v34, v33
	s_nop 1
	v_cndmask_b32_e32 v34, v32, v34, vcc
	v_lshlrev_b32_e32 v70, 2, v34
	v_xor_b32_e32 v34, 8, v32
	v_cmp_lt_i32_e32 vcc, v34, v33
	s_nop 1
	v_cndmask_b32_e32 v34, v32, v34, vcc
	v_lshlrev_b32_e32 v71, 2, v34
	v_xor_b32_e32 v34, 16, v32
	v_cmp_lt_i32_e32 vcc, v34, v33
	s_nop 1
	v_cndmask_b32_e32 v34, v32, v34, vcc
	v_lshlrev_b32_e32 v72, 2, v34
	v_xor_b32_e32 v34, 32, v32
	v_cmp_lt_i32_e32 vcc, v34, v33
	s_nop 1
	v_cndmask_b32_e32 v32, v32, v34, vcc
	v_lshlrev_b32_e32 v73, 2, v32
	s_branch .LBB0_1544
